# plus chunkprep forward substitution: matrix rows requested from LDS two steps ahead into rotating register buffers (all three passes)
# baseline (speedup 1.0000x reference)
; __device__ __forceinline__ unsigned pk2n(float lo, float hi) { return __builtin_bit_cast(unsigned, __builtin_convertvector((f32x2){lo, hi}, bf16v2)); }
; __device__ __forceinline__ void chunkprep_phase(const Params& P, LAS unsigned char* lds) {
;     ...
;                 for (int tt = 0; tt < 16; ++tt) {
;                     float acc = (pass < 2) ? be[tt] * Kf[tt * 132 + col] : ((tt == lane) ? 1.f : 0.f);
; #pragma unroll
;                     for (int s = 0; s < tt; ++s) acc -= Am[tt * 16 + s] * x[s];
;                     x[tt] = acc;
;                     if (pass < 2) Wb[tt * 136 + col] = (bf16_t)(pk2n(acc, 0.f) & 0xffffu); else Tt[tt * 17 + lane] = acc; }
.LBB0_466:
	ds_read_b32 v174, v92 offset:12864
	ds_read_b64 v[202:203], v92 offset:12928
	s_mov_b64 s[26:27], -1
	s_and_b64 vcc, exec, s[46:47]
	s_cbranch_vccz .LBB0_468
	ds_write_b32 v97, v2 offset:14912
	s_mov_b64 s[26:27], 0

; __device__ __forceinline__ unsigned pk2n(float lo, float hi) { return __builtin_bit_cast(unsigned, __builtin_convertvector((f32x2){lo, hi}, bf16v2)); }
; __device__ __forceinline__ void chunkprep_phase(const Params& P, LAS unsigned char* lds) {
;     ...
;                 for (int tt = 0; tt < 16; ++tt) {
;                     float acc = (pass < 2) ? be[tt] * Kf[tt * 132 + col] : ((tt == lane) ? 1.f : 0.f);
; #pragma unroll
;                     for (int s = 0; s < tt; ++s) acc -= Am[tt * 16 + s] * x[s];
;                     x[tt] = acc;
;                     if (pass < 2) Wb[tt * 136 + col] = (bf16_t)(pk2n(acc, 0.f) & 0xffffu); else Tt[tt * 17 + lane] = acc; }
.LBB0_472:
	ds_read_b96 v[158:160], v92 offset:12992
	v_cndmask_b32_e64 v15, 0, 1, s[46:47]
	v_cmp_ne_u32_e64 s[26:27], 1, v15
	s_andn2_b64 vcc, exec, s[46:47]
	s_mov_b64 s[46:47], -1
	s_waitcnt lgkmcnt(2)
	v_fma_f32 v13, -v2, v174, v13
	s_cbranch_vccnz .LBB0_532
	ds_write_b32 v97, v13 offset:14980
	s_cbranch_execz .LBB0_533

; __device__ __forceinline__ unsigned pk2n(float lo, float hi) { return __builtin_bit_cast(unsigned, __builtin_convertvector((f32x2){lo, hi}, bf16v2)); }
; __device__ __forceinline__ void chunkprep_phase(const Params& P, LAS unsigned char* lds) {
;     ...
;                 for (int tt = 0; tt < 16; ++tt) {
;                     float acc = (pass < 2) ? be[tt] * Kf[tt * 132 + col] : ((tt == lane) ? 1.f : 0.f);
; #pragma unroll
;                     for (int s = 0; s < tt; ++s) acc -= Am[tt * 16 + s] * x[s];
;                     x[tt] = acc;
;                     if (pass < 2) Wb[tt * 136 + col] = (bf16_t)(pk2n(acc, 0.f) & 0xffffu); else Tt[tt * 17 + lane] = acc; }
.LBB0_476:
	ds_read_b128 v[174:177], v92 offset:13056
	s_and_b64 vcc, exec, s[26:27]
	s_mov_b64 s[46:47], -1
	s_waitcnt lgkmcnt(2)
	v_fma_f32 v14, -v2, v202, v14
	v_fma_f32 v14, -v13, v203, v14
	s_cbranch_vccnz .LBB0_534
	ds_write_b32 v97, v14 offset:15048
	s_cbranch_execz .LBB0_535

; __device__ __forceinline__ unsigned pk2n(float lo, float hi) { return __builtin_bit_cast(unsigned, __builtin_convertvector((f32x2){lo, hi}, bf16v2)); }
; __device__ __forceinline__ void chunkprep_phase(const Params& P, LAS unsigned char* lds) {
;     ...
;                 for (int tt = 0; tt < 16; ++tt) {
;                     float acc = (pass < 2) ? be[tt] * Kf[tt * 132 + col] : ((tt == lane) ? 1.f : 0.f);
; #pragma unroll
;                     for (int s = 0; s < tt; ++s) acc -= Am[tt * 16 + s] * x[s];
;                     x[tt] = acc;
;                     if (pass < 2) Wb[tt * 136 + col] = (bf16_t)(pk2n(acc, 0.f) & 0xffffu); else Tt[tt * 17 + lane] = acc; }
.LBB0_480:
	ds_read_b128 v[202:205], v92 offset:13120
	ds_read_b32 v206, v92 offset:13136
	s_and_b64 vcc, exec, s[26:27]
	s_mov_b64 s[46:47], -1
	s_waitcnt lgkmcnt(3)
	v_fma_f32 v15, -v2, v158, v15
	v_fma_f32 v15, -v13, v159, v15
	v_fma_f32 v15, -v14, v160, v15
	s_cbranch_vccnz .LBB0_536
	ds_write_b32 v97, v15 offset:15116
	s_cbranch_execz .LBB0_537

; __device__ __forceinline__ unsigned pk2n(float lo, float hi) { return __builtin_bit_cast(unsigned, __builtin_convertvector((f32x2){lo, hi}, bf16v2)); }
; __device__ __forceinline__ void chunkprep_phase(const Params& P, LAS unsigned char* lds) {
;     ...
;                 for (int tt = 0; tt < 16; ++tt) {
;                     float acc = (pass < 2) ? be[tt] * Kf[tt * 132 + col] : ((tt == lane) ? 1.f : 0.f);
; #pragma unroll
;                     for (int s = 0; s < tt; ++s) acc -= Am[tt * 16 + s] * x[s];
;                     x[tt] = acc;
;                     if (pass < 2) Wb[tt * 136 + col] = (bf16_t)(pk2n(acc, 0.f) & 0xffffu); else Tt[tt * 17 + lane] = acc; }
.LBB0_484:
	ds_read_b128 v[158:161], v92 offset:13184
	ds_read_b64 v[162:163], v92 offset:13200
	s_and_b64 vcc, exec, s[26:27]
	s_mov_b64 s[46:47], -1
	s_waitcnt lgkmcnt(4)
	v_fma_f32 v16, -v2, v174, v16
	v_fma_f32 v16, -v13, v175, v16
	v_fma_f32 v16, -v14, v176, v16
	v_fma_f32 v16, -v15, v177, v16
	s_cbranch_vccnz .LBB0_538
	ds_write_b32 v97, v16 offset:15184
	s_cbranch_execz .LBB0_539

; __device__ __forceinline__ unsigned pk2n(float lo, float hi) { return __builtin_bit_cast(unsigned, __builtin_convertvector((f32x2){lo, hi}, bf16v2)); }
; __device__ __forceinline__ void chunkprep_phase(const Params& P, LAS unsigned char* lds) {
;     ...
;                 for (int tt = 0; tt < 16; ++tt) {
;                     float acc = (pass < 2) ? be[tt] * Kf[tt * 132 + col] : ((tt == lane) ? 1.f : 0.f);
; #pragma unroll
;                     for (int s = 0; s < tt; ++s) acc -= Am[tt * 16 + s] * x[s];
;                     x[tt] = acc;
;                     if (pass < 2) Wb[tt * 136 + col] = (bf16_t)(pk2n(acc, 0.f) & 0xffffu); else Tt[tt * 17 + lane] = acc; }
.LBB0_488:
	ds_read_b128 v[174:177], v92 offset:13248
	ds_read_b96 v[178:180], v92 offset:13264
	s_and_b64 vcc, exec, s[26:27]
	s_mov_b64 s[46:47], -1
	s_waitcnt lgkmcnt(4)
	v_fma_f32 v17, -v2, v202, v17
	v_fma_f32 v17, -v13, v203, v17
	v_fma_f32 v17, -v14, v204, v17
	v_fma_f32 v17, -v15, v205, v17
	v_fma_f32 v17, -v16, v206, v17
	s_cbranch_vccnz .LBB0_540
	ds_write_b32 v97, v17 offset:15252
	s_cbranch_execz .LBB0_541

; __device__ __forceinline__ unsigned pk2n(float lo, float hi) { return __builtin_bit_cast(unsigned, __builtin_convertvector((f32x2){lo, hi}, bf16v2)); }
; __device__ __forceinline__ void chunkprep_phase(const Params& P, LAS unsigned char* lds) {
;     ...
;                 for (int tt = 0; tt < 16; ++tt) {
;                     float acc = (pass < 2) ? be[tt] * Kf[tt * 132 + col] : ((tt == lane) ? 1.f : 0.f);
; #pragma unroll
;                     for (int s = 0; s < tt; ++s) acc -= Am[tt * 16 + s] * x[s];
;                     x[tt] = acc;
;                     if (pass < 2) Wb[tt * 136 + col] = (bf16_t)(pk2n(acc, 0.f) & 0xffffu); else Tt[tt * 17 + lane] = acc; }
.LBB0_492:
	ds_read_b128 v[202:205], v92 offset:13312
	ds_read_b128 v[206:209], v92 offset:13328
	s_and_b64 vcc, exec, s[26:27]
	s_mov_b64 s[46:47], -1
	s_waitcnt lgkmcnt(4)
	v_fma_f32 v18, -v2, v158, v18
	v_fma_f32 v18, -v13, v159, v18
	v_fma_f32 v18, -v14, v160, v18
	v_fma_f32 v18, -v15, v161, v18
	v_fma_f32 v18, -v16, v162, v18
	v_fma_f32 v18, -v17, v163, v18
	s_cbranch_vccnz .LBB0_542
	ds_write_b32 v97, v18 offset:15320
	s_cbranch_execz .LBB0_543

; __device__ __forceinline__ unsigned pk2n(float lo, float hi) { return __builtin_bit_cast(unsigned, __builtin_convertvector((f32x2){lo, hi}, bf16v2)); }
; __device__ __forceinline__ void chunkprep_phase(const Params& P, LAS unsigned char* lds) {
;     ...
;                 for (int tt = 0; tt < 16; ++tt) {
;                     float acc = (pass < 2) ? be[tt] * Kf[tt * 132 + col] : ((tt == lane) ? 1.f : 0.f);
; #pragma unroll
;                     for (int s = 0; s < tt; ++s) acc -= Am[tt * 16 + s] * x[s];
;                     x[tt] = acc;
;                     if (pass < 2) Wb[tt * 136 + col] = (bf16_t)(pk2n(acc, 0.f) & 0xffffu); else Tt[tt * 17 + lane] = acc; }
.LBB0_496:
	ds_read_b128 v[158:161], v92 offset:13376
	ds_read_b128 v[162:165], v92 offset:13392
	ds_read_b32 v166, v92 offset:13408
	s_and_b64 vcc, exec, s[26:27]
	s_mov_b64 s[46:47], -1
	s_waitcnt lgkmcnt(5)
	v_fma_f32 v19, -v2, v174, v19
	v_fma_f32 v19, -v13, v175, v19
	v_fma_f32 v19, -v14, v176, v19
	v_fma_f32 v19, -v15, v177, v19
	v_fma_f32 v19, -v16, v178, v19
	v_fma_f32 v19, -v17, v179, v19
	v_fma_f32 v19, -v18, v180, v19
	s_cbranch_vccnz .LBB0_544
	ds_write_b32 v97, v19 offset:15388
	s_cbranch_execz .LBB0_545

; __device__ __forceinline__ unsigned pk2n(float lo, float hi) { return __builtin_bit_cast(unsigned, __builtin_convertvector((f32x2){lo, hi}, bf16v2)); }
; __device__ __forceinline__ void chunkprep_phase(const Params& P, LAS unsigned char* lds) {
;     ...
;                 for (int tt = 0; tt < 16; ++tt) {
;                     float acc = (pass < 2) ? be[tt] * Kf[tt * 132 + col] : ((tt == lane) ? 1.f : 0.f);
; #pragma unroll
;                     for (int s = 0; s < tt; ++s) acc -= Am[tt * 16 + s] * x[s];
;                     x[tt] = acc;
;                     if (pass < 2) Wb[tt * 136 + col] = (bf16_t)(pk2n(acc, 0.f) & 0xffffu); else Tt[tt * 17 + lane] = acc; }
.LBB0_500:
	ds_read_b128 v[174:177], v92 offset:13440
	ds_read_b128 v[178:181], v92 offset:13456
	ds_read_b64 v[182:183], v92 offset:13472
	s_and_b64 vcc, exec, s[26:27]
	s_mov_b64 s[46:47], -1
	s_waitcnt lgkmcnt(6)
	v_fma_f32 v20, -v2, v202, v20
	v_fma_f32 v20, -v13, v203, v20
	v_fma_f32 v20, -v14, v204, v20
	v_fma_f32 v20, -v15, v205, v20
	v_fma_f32 v20, -v16, v206, v20
	v_fma_f32 v20, -v17, v207, v20
	v_fma_f32 v20, -v18, v208, v20
	v_fma_f32 v20, -v19, v209, v20
	s_cbranch_vccnz .LBB0_546
	ds_write_b32 v97, v20 offset:15456
	s_cbranch_execz .LBB0_547

; __device__ __forceinline__ unsigned pk2n(float lo, float hi) { return __builtin_bit_cast(unsigned, __builtin_convertvector((f32x2){lo, hi}, bf16v2)); }
; __device__ __forceinline__ void chunkprep_phase(const Params& P, LAS unsigned char* lds) {
;     ...
;                 for (int tt = 0; tt < 16; ++tt) {
;                     float acc = (pass < 2) ? be[tt] * Kf[tt * 132 + col] : ((tt == lane) ? 1.f : 0.f);
; #pragma unroll
;                     for (int s = 0; s < tt; ++s) acc -= Am[tt * 16 + s] * x[s];
;                     x[tt] = acc;
;                     if (pass < 2) Wb[tt * 136 + col] = (bf16_t)(pk2n(acc, 0.f) & 0xffffu); else Tt[tt * 17 + lane] = acc; }
.LBB0_504:
	ds_read_b128 v[202:205], v92 offset:13504
	ds_read_b128 v[206:209], v92 offset:13520
	ds_read_b96 v[210:212], v92 offset:13536
	s_and_b64 vcc, exec, s[26:27]
	s_mov_b64 s[46:47], -1
	s_waitcnt lgkmcnt(6)
	v_fma_f32 v21, -v2, v158, v21
	v_fma_f32 v21, -v13, v159, v21
	v_fma_f32 v21, -v14, v160, v21
	v_fma_f32 v21, -v15, v161, v21
	v_fma_f32 v21, -v16, v162, v21
	v_fma_f32 v21, -v17, v163, v21
	v_fma_f32 v21, -v18, v164, v21
	v_fma_f32 v21, -v19, v165, v21
	v_fma_f32 v21, -v20, v166, v21
	s_cbranch_vccnz .LBB0_548
	ds_write_b32 v97, v21 offset:15524
	s_cbranch_execz .LBB0_549

; __device__ __forceinline__ unsigned pk2n(float lo, float hi) { return __builtin_bit_cast(unsigned, __builtin_convertvector((f32x2){lo, hi}, bf16v2)); }
; __device__ __forceinline__ void chunkprep_phase(const Params& P, LAS unsigned char* lds) {
;     ...
;                 for (int tt = 0; tt < 16; ++tt) {
;                     float acc = (pass < 2) ? be[tt] * Kf[tt * 132 + col] : ((tt == lane) ? 1.f : 0.f);
; #pragma unroll
;                     for (int s = 0; s < tt; ++s) acc -= Am[tt * 16 + s] * x[s];
;                     x[tt] = acc;
;                     if (pass < 2) Wb[tt * 136 + col] = (bf16_t)(pk2n(acc, 0.f) & 0xffffu); else Tt[tt * 17 + lane] = acc; }
.LBB0_508:
	ds_read_b128 v[158:161], v92 offset:13568
	ds_read_b128 v[162:165], v92 offset:13584
	ds_read_b128 v[166:169], v92 offset:13600
	s_and_b64 vcc, exec, s[26:27]
	s_mov_b64 s[46:47], -1
	s_waitcnt lgkmcnt(6)
	v_fma_f32 v22, -v2, v174, v22
	v_fma_f32 v22, -v13, v175, v22
	v_fma_f32 v22, -v14, v176, v22
	v_fma_f32 v22, -v15, v177, v22
	v_fma_f32 v22, -v16, v178, v22
	v_fma_f32 v22, -v17, v179, v22
	v_fma_f32 v22, -v18, v180, v22
	v_fma_f32 v22, -v19, v181, v22
	v_fma_f32 v22, -v20, v182, v22
	v_fma_f32 v22, -v21, v183, v22
	s_cbranch_vccnz .LBB0_550
	ds_write_b32 v97, v22 offset:15592
	s_cbranch_execz .LBB0_551

; __device__ __forceinline__ unsigned pk2n(float lo, float hi) { return __builtin_bit_cast(unsigned, __builtin_convertvector((f32x2){lo, hi}, bf16v2)); }
; __device__ __forceinline__ void chunkprep_phase(const Params& P, LAS unsigned char* lds) {
;     ...
;                 for (int tt = 0; tt < 16; ++tt) {
;                     float acc = (pass < 2) ? be[tt] * Kf[tt * 132 + col] : ((tt == lane) ? 1.f : 0.f);
; #pragma unroll
;                     for (int s = 0; s < tt; ++s) acc -= Am[tt * 16 + s] * x[s];
;                     x[tt] = acc;
;                     if (pass < 2) Wb[tt * 136 + col] = (bf16_t)(pk2n(acc, 0.f) & 0xffffu); else Tt[tt * 17 + lane] = acc; }
.LBB0_512:
	ds_read_b128 v[174:177], v92 offset:13632
	ds_read_b128 v[178:181], v92 offset:13648
	ds_read_b128 v[182:185], v92 offset:13664
	ds_read_b32 v186, v92 offset:13680
	s_and_b64 vcc, exec, s[26:27]
	s_mov_b64 s[46:47], -1
	s_waitcnt lgkmcnt(7)
	v_fma_f32 v23, -v2, v202, v23
	v_fma_f32 v23, -v13, v203, v23
	v_fma_f32 v23, -v14, v204, v23
	v_fma_f32 v23, -v15, v205, v23
	v_fma_f32 v23, -v16, v206, v23
	v_fma_f32 v23, -v17, v207, v23
	v_fma_f32 v23, -v18, v208, v23
	v_fma_f32 v23, -v19, v209, v23
	v_fma_f32 v23, -v20, v210, v23
	v_fma_f32 v23, -v21, v211, v23
	v_fma_f32 v23, -v22, v212, v23
	s_cbranch_vccnz .LBB0_552
	ds_write_b32 v97, v23 offset:15660
	s_cbranch_execz .LBB0_553

; __device__ __forceinline__ unsigned pk2n(float lo, float hi) { return __builtin_bit_cast(unsigned, __builtin_convertvector((f32x2){lo, hi}, bf16v2)); }
; __device__ __forceinline__ void chunkprep_phase(const Params& P, LAS unsigned char* lds) {
;     ...
;                 for (int tt = 0; tt < 16; ++tt) {
;                     float acc = (pass < 2) ? be[tt] * Kf[tt * 132 + col] : ((tt == lane) ? 1.f : 0.f);
; #pragma unroll
;                     for (int s = 0; s < tt; ++s) acc -= Am[tt * 16 + s] * x[s];
;                     x[tt] = acc;
;                     if (pass < 2) Wb[tt * 136 + col] = (bf16_t)(pk2n(acc, 0.f) & 0xffffu); else Tt[tt * 17 + lane] = acc; }
.LBB0_516:
	ds_read_b128 v[202:205], v92 offset:13696
	ds_read_b128 v[206:209], v92 offset:13712
	ds_read_b128 v[210:213], v92 offset:13728
	ds_read_b64 v[214:215], v92 offset:13744
	s_and_b64 vcc, exec, s[26:27]
	s_mov_b64 s[46:47], -1
	s_waitcnt lgkmcnt(8)
	v_fma_f32 v24, -v2, v158, v24
	v_fma_f32 v24, -v13, v159, v24
	v_fma_f32 v24, -v14, v160, v24
	v_fma_f32 v24, -v15, v161, v24
	v_fma_f32 v24, -v16, v162, v24
	v_fma_f32 v24, -v17, v163, v24
	v_fma_f32 v24, -v18, v164, v24
	v_fma_f32 v24, -v19, v165, v24
	v_fma_f32 v24, -v20, v166, v24
	v_fma_f32 v24, -v21, v167, v24
	v_fma_f32 v24, -v22, v168, v24
	v_fma_f32 v24, -v23, v169, v24
	s_cbranch_vccnz .LBB0_554
	ds_write_b32 v97, v24 offset:15728
	s_cbranch_execz .LBB0_555

; __device__ __forceinline__ unsigned pk2n(float lo, float hi) { return __builtin_bit_cast(unsigned, __builtin_convertvector((f32x2){lo, hi}, bf16v2)); }
; __device__ __forceinline__ void chunkprep_phase(const Params& P, LAS unsigned char* lds) {
;     ...
;                 for (int tt = 0; tt < 16; ++tt) {
;                     float acc = (pass < 2) ? be[tt] * Kf[tt * 132 + col] : ((tt == lane) ? 1.f : 0.f);
; #pragma unroll
;                     for (int s = 0; s < tt; ++s) acc -= Am[tt * 16 + s] * x[s];
;                     x[tt] = acc;
;                     if (pass < 2) Wb[tt * 136 + col] = (bf16_t)(pk2n(acc, 0.f) & 0xffffu); else Tt[tt * 17 + lane] = acc; }
.LBB0_520:
	ds_read_b128 v[158:161], v92 offset:13760
	ds_read_b128 v[162:165], v92 offset:13776
	ds_read_b128 v[166:169], v92 offset:13792
	ds_read_b96 v[170:172], v92 offset:13808
	s_and_b64 vcc, exec, s[26:27]
	s_waitcnt lgkmcnt(8)
	v_fma_f32 v25, -v2, v174, v25
	v_fma_f32 v25, -v13, v175, v25
	v_fma_f32 v25, -v14, v176, v25
	v_fma_f32 v25, -v15, v177, v25
	v_fma_f32 v25, -v16, v178, v25
	v_fma_f32 v25, -v17, v179, v25
	v_fma_f32 v25, -v18, v180, v25
	v_fma_f32 v25, -v19, v181, v25
	v_fma_f32 v25, -v20, v182, v25
	v_fma_f32 v25, -v21, v183, v25
	v_fma_f32 v25, -v22, v184, v25
	v_fma_f32 v25, -v23, v185, v25
	v_fma_f32 v25, -v24, v186, v25
	s_mov_b64 s[46:47], -1
	s_cbranch_vccnz .LBB0_556
	ds_write_b32 v97, v25 offset:15796
	s_cbranch_execz .LBB0_557

; __device__ __forceinline__ unsigned pk2n(float lo, float hi) { return __builtin_bit_cast(unsigned, __builtin_convertvector((f32x2){lo, hi}, bf16v2)); }
; __device__ __forceinline__ void chunkprep_phase(const Params& P, LAS unsigned char* lds) {
;     ...
;                 for (int tt = 0; tt < 16; ++tt) {
;                     float acc = (pass < 2) ? be[tt] * Kf[tt * 132 + col] : ((tt == lane) ? 1.f : 0.f);
; #pragma unroll
;                     for (int s = 0; s < tt; ++s) acc -= Am[tt * 16 + s] * x[s];
;                     x[tt] = acc;
;                     if (pass < 2) Wb[tt * 136 + col] = (bf16_t)(pk2n(acc, 0.f) & 0xffffu); else Tt[tt * 17 + lane] = acc; }
.LBB0_524:
	s_and_b64 vcc, exec, s[26:27]
	s_waitcnt lgkmcnt(4)
	v_fma_f32 v26, -v2, v202, v26
	v_fma_f32 v26, -v13, v203, v26
	v_fma_f32 v26, -v14, v204, v26
	v_fma_f32 v26, -v15, v205, v26
	v_fma_f32 v26, -v16, v206, v26
	v_fma_f32 v26, -v17, v207, v26
	v_fma_f32 v26, -v18, v208, v26
	v_fma_f32 v26, -v19, v209, v26
	v_fma_f32 v26, -v20, v210, v26
	v_fma_f32 v26, -v21, v211, v26
	v_fma_f32 v26, -v22, v212, v26
	v_fma_f32 v26, -v23, v213, v26
	v_fma_f32 v26, -v24, v214, v26
	v_fma_f32 v26, -v25, v215, v26
	s_mov_b64 s[46:47], -1
	s_cbranch_vccnz .LBB0_558
	ds_write_b32 v97, v26 offset:15864
	s_cbranch_execz .LBB0_559

; __device__ __forceinline__ unsigned pk2n(float lo, float hi) { return __builtin_bit_cast(unsigned, __builtin_convertvector((f32x2){lo, hi}, bf16v2)); }
; __device__ __forceinline__ void chunkprep_phase(const Params& P, LAS unsigned char* lds) {
;     ...
;                 for (int tt = 0; tt < 16; ++tt) {
;                     float acc = (pass < 2) ? be[tt] * Kf[tt * 132 + col] : ((tt == lane) ? 1.f : 0.f);
; #pragma unroll
;                     for (int s = 0; s < tt; ++s) acc -= Am[tt * 16 + s] * x[s];
;                     x[tt] = acc;
;                     if (pass < 2) Wb[tt * 136 + col] = (bf16_t)(pk2n(acc, 0.f) & 0xffffu); else Tt[tt * 17 + lane] = acc; }
.LBB0_528:
	s_and_b64 vcc, exec, s[26:27]
	s_waitcnt lgkmcnt(0)
	v_fma_f32 v2, -v2, v158, v27
	v_fma_f32 v2, -v13, v159, v2
	v_fma_f32 v2, -v14, v160, v2
	v_fma_f32 v2, -v15, v161, v2
	v_fma_f32 v2, -v16, v162, v2
	v_fma_f32 v2, -v17, v163, v2
	v_fma_f32 v2, -v18, v164, v2
	v_fma_f32 v2, -v19, v165, v2
	v_fma_f32 v2, -v20, v166, v2
	v_fma_f32 v2, -v21, v167, v2
	v_fma_f32 v2, -v22, v168, v2
	v_fma_f32 v2, -v23, v169, v2
	v_fma_f32 v2, -v24, v170, v2
	v_fma_f32 v2, -v25, v171, v2
	v_fma_f32 v2, -v26, v172, v2
	s_mov_b64 s[24:25], -1
	s_cbranch_vccnz .LBB0_530
	s_mov_b64 s[24:25], 0
	ds_write_b32 v97, v2 offset:15932
